# grid barrier followers issue their L1 invalidate (buffer_inv sc1) before the spin instead of after release; the XCD leader still invalidates after release
# speedup vs baseline: 1.0221x; 1.0124x over previous
.LBB0_179:
	s_lshl_b32 s20, s36, 6
	s_add_i32 s2, s20, 0x500
	s_mov_b32 s3, 0
	s_lshl_b64 s[0:1], s[2:3], 2
	s_add_u32 s0, s34, s0
	s_addc_u32 s1, s35, s1
	v_mov_b32_e32 v1, 1
	v_mov_b64_e32 v[4:5], s[0:1]
	flat_atomic_add v1, v[4:5], v1 sc0
	v_cvt_f32_u32_e32 v3, v2
	v_sub_u32_e32 v4, 0, v2
	v_rcp_iflag_f32_e32 v3, v3
	s_nop 0
	v_mul_f32_e32 v3, 0x4f7ffffe, v3
	v_cvt_u32_f32_e32 v3, v3
	v_mul_lo_u32 v4, v4, v3
	v_mul_hi_u32 v4, v3, v4
	v_add_u32_e32 v3, v3, v4
	s_waitcnt vmcnt(0) lgkmcnt(0)
	v_mul_hi_u32 v3, v1, v3
	v_mul_lo_u32 v5, v3, v2
	v_add_u32_e32 v4, 1, v1
	v_sub_u32_e32 v1, v1, v5
	v_add_u32_e32 v6, 1, v3
	v_cmp_ge_u32_e32 vcc, v1, v2
	v_sub_u32_e32 v5, v1, v2
	s_nop 0
	v_cndmask_b32_e32 v3, v3, v6, vcc
	v_cndmask_b32_e32 v1, v1, v5, vcc
	v_add_u32_e32 v5, 1, v3
	v_cmp_ge_u32_e32 vcc, v1, v2
	s_nop 1
	v_cndmask_b32_e32 v1, v3, v5, vcc
	v_mad_u64_u32 v[2:3], s[0:1], v2, v1, v[2:3]
	v_cmp_ne_u32_e32 vcc, v4, v2
	s_and_saveexec_b64 s[0:1], vcc
	s_xor_b64 s[0:1], exec, s[0:1]
	s_cbranch_execz .LBB0_192
	buffer_inv sc1
	s_nop 0
	s_nop 0
	s_nop 0
	s_nop 0
	s_nop 0
	s_nop 0
	s_nop 0
	s_nop 0
	s_nop 0
	s_nop 0
	s_nop 0
	s_nop 0
	s_nop 0
	s_nop 0
	s_add_i32 s2, s20, 0x900
	s_lshl_b64 s[2:3], s[2:3], 2
	s_add_u32 s4, s34, s2
	s_addc_u32 s5, s35, s3
	v_mov_b64_e32 v[2:3], s[4:5]
	global_load_dword v0, v[2:3], off sc1
	s_waitcnt vmcnt(0) lgkmcnt(0)
	v_cmp_eq_u32_e32 vcc, v0, v1
	s_and_saveexec_b64 s[2:3], vcc
	s_cbranch_execz .LBB0_191
	s_mov_b32 s21, 1
	s_mov_b64 s[6:7], 0
	s_branch .LBB0_183

.LBB0_191:
	s_or_b64 exec, exec, s[2:3]
	s_waitcnt vmcnt(0) lgkmcnt(0)
	s_nop 0
	s_nop 0
	s_waitcnt vmcnt(0)

.LBB0_243:
	s_lshl_b32 s20, s33, 6
	s_add_i32 s84, s20, 0x500
	s_lshl_b64 s[0:1], s[84:85], 2
	s_add_u32 s0, s34, s0
	s_addc_u32 s1, s35, s1
	v_mov_b64_e32 v[4:5], s[0:1]
	flat_atomic_add v3, v[4:5], v171 sc0
	v_cvt_f32_u32_e32 v1, v2
	v_sub_u32_e32 v4, 0, v2
	v_rcp_iflag_f32_e32 v1, v1
	s_nop 0
	v_mul_f32_e32 v1, 0x4f7ffffe, v1
	v_cvt_u32_f32_e32 v1, v1
	v_mul_lo_u32 v4, v4, v1
	v_mul_hi_u32 v4, v1, v4
	v_add_u32_e32 v1, v1, v4
	s_waitcnt vmcnt(0) lgkmcnt(0)
	v_mul_hi_u32 v1, v3, v1
	v_mul_lo_u32 v4, v1, v2
	v_sub_u32_e32 v4, v3, v4
	v_cmp_ge_u32_e32 vcc, v4, v2
	v_add_u32_e32 v5, 1, v1
	s_nop 0
	v_cndmask_b32_e32 v1, v1, v5, vcc
	v_sub_u32_e32 v5, v4, v2
	v_cndmask_b32_e32 v4, v4, v5, vcc
	v_cmp_ge_u32_e32 vcc, v4, v2
	v_add_u32_e32 v4, 1, v1
	s_nop 0
	v_cndmask_b32_e32 v1, v1, v4, vcc
	v_add_u32_e32 v4, 1, v3
	v_mad_u64_u32 v[2:3], s[0:1], v2, v1, v[2:3]
	v_cmp_ne_u32_e32 vcc, v4, v2
	s_and_saveexec_b64 s[0:1], vcc
	s_xor_b64 s[0:1], exec, s[0:1]
	s_cbranch_execz .LBB0_256
	buffer_inv sc1
	s_nop 0
	s_nop 0
	s_nop 0
	s_nop 0
	s_nop 0
	s_nop 0
	s_nop 0
	s_nop 0
	s_nop 0
	s_nop 0
	s_nop 0
	s_nop 0
	s_nop 0
	s_nop 0
	s_add_i32 s84, s20, 0x900
	s_lshl_b64 s[2:3], s[84:85], 2
	s_add_u32 s4, s34, s2
	s_addc_u32 s5, s35, s3
	v_mov_b64_e32 v[2:3], s[4:5]
	global_load_dword v0, v[2:3], off sc1
	s_waitcnt vmcnt(0) lgkmcnt(0)
	v_cmp_eq_u32_e32 vcc, v0, v1
	s_and_saveexec_b64 s[2:3], vcc
	s_cbranch_execz .LBB0_255
	s_mov_b32 s21, 1
	s_mov_b64 s[6:7], 0
	s_branch .LBB0_247

.LBB0_759:
	s_lshl_b32 s20, s33, 6
	s_add_i32 s84, s20, 0x500
	s_lshl_b64 s[0:1], s[84:85], 2
	s_add_u32 s0, s36, s0
	s_addc_u32 s1, s37, s1
	v_mov_b64_e32 v[4:5], s[0:1]
	flat_atomic_add v3, v[4:5], v171 sc0
	v_cvt_f32_u32_e32 v1, v2
	v_sub_u32_e32 v4, 0, v2
	v_rcp_iflag_f32_e32 v1, v1
	s_nop 0
	v_mul_f32_e32 v1, 0x4f7ffffe, v1
	v_cvt_u32_f32_e32 v1, v1
	v_mul_lo_u32 v4, v4, v1
	v_mul_hi_u32 v4, v1, v4
	v_add_u32_e32 v1, v1, v4
	s_waitcnt vmcnt(0) lgkmcnt(0)
	v_mul_hi_u32 v1, v3, v1
	v_mul_lo_u32 v4, v1, v2
	v_sub_u32_e32 v4, v3, v4
	v_cmp_ge_u32_e32 vcc, v4, v2
	v_add_u32_e32 v5, 1, v1
	s_nop 0
	v_cndmask_b32_e32 v1, v1, v5, vcc
	v_sub_u32_e32 v5, v4, v2
	v_cndmask_b32_e32 v4, v4, v5, vcc
	v_cmp_ge_u32_e32 vcc, v4, v2
	v_add_u32_e32 v4, 1, v1
	s_nop 0
	v_cndmask_b32_e32 v1, v1, v4, vcc
	v_add_u32_e32 v4, 1, v3
	v_mad_u64_u32 v[2:3], s[0:1], v2, v1, v[2:3]
	v_cmp_ne_u32_e32 vcc, v4, v2
	s_and_saveexec_b64 s[0:1], vcc
	s_xor_b64 s[0:1], exec, s[0:1]
	s_cbranch_execz .LBB0_772
	buffer_inv sc1
	s_nop 0
	s_nop 0
	s_nop 0
	s_nop 0
	s_nop 0
	s_nop 0
	s_nop 0
	s_nop 0
	s_nop 0
	s_nop 0
	s_nop 0
	s_nop 0
	s_nop 0
	s_nop 0
	s_add_i32 s84, s20, 0x900
	s_lshl_b64 s[2:3], s[84:85], 2
	s_add_u32 s4, s36, s2
	s_addc_u32 s5, s37, s3
	v_mov_b64_e32 v[2:3], s[4:5]
	global_load_dword v0, v[2:3], off sc1
	s_waitcnt vmcnt(0) lgkmcnt(0)
	v_cmp_eq_u32_e32 vcc, v0, v1
	s_and_saveexec_b64 s[2:3], vcc
	s_cbranch_execz .LBB0_771
	s_mov_b32 s21, 1
	s_mov_b64 s[6:7], 0
	s_branch .LBB0_763
